# accumulator zeroing via v_mov_b64 (64 instead of 128 VALU per tile) on top of setprio removal
# speedup vs baseline: 1.0068x; 1.0010x over previous
; template <class Epi, class Sched, bool ALIGN_EPI = false, bool SP2 = false>
; __device__ __forceinline__ void gemm_phase(LAS unsigned char* lds, const Gemm g, const Sched S, const Epi E) {
;     ...
;         const bool has_next = S.next(ui + 1, nxt);
;         const char* nA = has_next ? (const char*)g.A + (size_t)nxt.pm * tstep : cA; const char* nB = has_next ? (const char*)g.Bt + (size_t)nxt.pn * tstep : cB;
;     ...
; #pragma unroll
;         for (int a = 0; a < 2; ++a)
; #pragma unroll
;             for (int b = 0; b < 2; ++b)
; #pragma unroll
;                 for (int m = 0; m < 4; ++m)
; #pragma unroll
;                     for (int n = 0; n < 2; ++n) acc[a][b][m][n] = (f32x4){0.f, 0.f, 0.f, 0.f};
;         cur = nxt; cA = nA; cB = nB; ++ui;
.LBB0_105:
	s_ashr_i32 s25, s24, 31
	s_lshl_b64 s[26:27], s[24:25], 20
	s_add_u32 s26, s12, s26
	s_addc_u32 s27, s13, s27
	s_and_b64 s[34:35], s[2:3], exec
	s_cselect_b32 s25, s27, s41
	s_cselect_b32 s45, s26, s40
	s_ashr_i32 s23, s22, 31
	s_lshl_b64 s[34:35], s[22:23], 20
	s_add_u32 s34, s64, s34
	s_addc_u32 s35, s65, s35
	s_and_b64 s[46:47], s[2:3], exec
	s_cselect_b32 s23, s35, s39
	s_cselect_b32 s46, s34, s38
	v_lshl_add_u32 v144, s36, 8, v148
	s_add_u32 s36, s40, 0x80080
	s_addc_u32 s37, s41, 0
	s_add_u32 s47, s38, 0x100
	s_addc_u32 s48, s39, 0
	v_readlane_b32 s38, v254, 28
	v_ashrrev_i32_e32 v145, 31, v144
	v_mov_b32_e32 v0, 0
	v_readlane_b32 s39, v254, 29
	s_mov_b32 s49, -2
	v_mov_b64_e32 v[0:1], 0
	v_mov_b64_e32 v[2:3], 0
	v_mov_b64_e32 v[4:5], 0
	v_mov_b64_e32 v[6:7], 0
	v_mov_b64_e32 v[8:9], 0
	v_mov_b64_e32 v[10:11], 0
	v_mov_b64_e32 v[12:13], 0
	v_mov_b64_e32 v[14:15], 0
	v_mov_b64_e32 v[16:17], 0
	v_mov_b64_e32 v[18:19], 0
	v_mov_b64_e32 v[20:21], 0
	v_mov_b64_e32 v[22:23], 0
	v_mov_b64_e32 v[24:25], 0
	v_mov_b64_e32 v[26:27], 0
	v_mov_b64_e32 v[28:29], 0
	v_mov_b64_e32 v[30:31], 0
	v_mov_b64_e32 v[32:33], 0
	v_mov_b64_e32 v[34:35], 0
	v_mov_b64_e32 v[36:37], 0
	v_mov_b64_e32 v[38:39], 0
	v_mov_b64_e32 v[40:41], 0
	v_mov_b64_e32 v[42:43], 0
	v_mov_b64_e32 v[44:45], 0
	v_mov_b64_e32 v[46:47], 0
	v_mov_b64_e32 v[48:49], 0
	v_mov_b64_e32 v[50:51], 0
	v_mov_b64_e32 v[52:53], 0
	v_mov_b64_e32 v[54:55], 0
	v_mov_b64_e32 v[56:57], 0
	v_mov_b64_e32 v[58:59], 0
	v_mov_b64_e32 v[60:61], 0
	v_mov_b64_e32 v[62:63], 0
	v_mov_b64_e32 v[64:65], 0
	v_mov_b64_e32 v[66:67], 0
	v_mov_b64_e32 v[68:69], 0
	v_mov_b64_e32 v[70:71], 0
	v_mov_b64_e32 v[72:73], 0
	v_mov_b64_e32 v[74:75], 0
	v_mov_b64_e32 v[76:77], 0
	v_mov_b64_e32 v[78:79], 0
	v_mov_b64_e32 v[80:81], 0
	v_mov_b64_e32 v[82:83], 0
	v_mov_b64_e32 v[84:85], 0
	v_mov_b64_e32 v[86:87], 0
	v_mov_b64_e32 v[88:89], 0
	v_mov_b64_e32 v[90:91], 0
	v_mov_b64_e32 v[92:93], 0
	v_mov_b64_e32 v[94:95], 0
	v_mov_b64_e32 v[96:97], 0
	v_mov_b64_e32 v[98:99], 0
	v_mov_b64_e32 v[100:101], 0
	v_mov_b64_e32 v[102:103], 0
	v_mov_b64_e32 v[104:105], 0
	v_mov_b64_e32 v[106:107], 0
	v_mov_b64_e32 v[108:109], 0
	v_mov_b64_e32 v[110:111], 0
	v_mov_b64_e32 v[112:113], 0
	v_mov_b64_e32 v[114:115], 0
	v_mov_b64_e32 v[116:117], 0
	v_mov_b64_e32 v[118:119], 0
	v_mov_b64_e32 v[120:121], 0
	v_mov_b64_e32 v[122:123], 0
	v_mov_b64_e32 v[124:125], 0
	v_mov_b64_e32 v[126:127], 0
	v_lshl_add_u64 v[146:147], v[144:145], 2, s[38:39]
	s_branch .LBB0_107

; template <class Epi, class Sched, bool ALIGN_EPI = false, bool SP2 = false>
; __device__ __forceinline__ void gemm_phase(LAS unsigned char* lds, const Gemm g, const Sched S, const Epi E) {
;     ...
; #pragma unroll
;         for (int a = 0; a < 2; ++a)
; #pragma unroll
;             for (int b = 0; b < 2; ++b)
; #pragma unroll
;                 for (int m = 0; m < 4; ++m)
; #pragma unroll
;                     for (int n = 0; n < 2; ++n) acc[a][b][m][n] = (f32x4){0.f, 0.f, 0.f, 0.f};
;         cur = nxt; cA = nA; cB = nB; ++ui;
.LBB0_192:
	s_add_u32 s34, s34, 0x158080
	s_addc_u32 s35, s35, 0
	s_add_u32 s46, s36, 0x100
	v_mov_b32_e32 v0, 0
	s_addc_u32 s47, s37, 0
	s_mov_b32 s48, -2
	s_waitcnt lgkmcnt(0)
	v_mov_b64_e32 v[0:1], 0
	v_mov_b64_e32 v[2:3], 0
	v_mov_b64_e32 v[4:5], 0
	v_mov_b64_e32 v[6:7], 0
	v_mov_b64_e32 v[8:9], 0
	v_mov_b64_e32 v[10:11], 0
	v_mov_b64_e32 v[12:13], 0
	v_mov_b64_e32 v[14:15], 0
	v_mov_b64_e32 v[16:17], 0
	v_mov_b64_e32 v[18:19], 0
	v_mov_b64_e32 v[20:21], 0
	v_mov_b64_e32 v[22:23], 0
	v_mov_b64_e32 v[24:25], 0
	v_mov_b64_e32 v[26:27], 0
	v_mov_b64_e32 v[28:29], 0
	v_mov_b64_e32 v[30:31], 0
	v_mov_b64_e32 v[32:33], 0
	v_mov_b64_e32 v[34:35], 0
	v_mov_b64_e32 v[36:37], 0
	v_mov_b64_e32 v[38:39], 0
	v_mov_b64_e32 v[40:41], 0
	v_mov_b64_e32 v[42:43], 0
	v_mov_b64_e32 v[44:45], 0
	v_mov_b64_e32 v[46:47], 0
	v_mov_b64_e32 v[48:49], 0
	v_mov_b64_e32 v[50:51], 0
	v_mov_b64_e32 v[52:53], 0
	v_mov_b64_e32 v[54:55], 0
	v_mov_b64_e32 v[56:57], 0
	v_mov_b64_e32 v[58:59], 0
	v_mov_b64_e32 v[60:61], 0
	v_mov_b64_e32 v[62:63], 0
	v_mov_b64_e32 v[64:65], 0
	v_mov_b64_e32 v[66:67], 0
	v_mov_b64_e32 v[68:69], 0
	v_mov_b64_e32 v[70:71], 0
	v_mov_b64_e32 v[72:73], 0
	v_mov_b64_e32 v[74:75], 0
	v_mov_b64_e32 v[76:77], 0
	v_mov_b64_e32 v[78:79], 0
	v_mov_b64_e32 v[80:81], 0
	v_mov_b64_e32 v[82:83], 0
	v_mov_b64_e32 v[84:85], 0
	v_mov_b64_e32 v[86:87], 0
	v_mov_b64_e32 v[88:89], 0
	v_mov_b64_e32 v[90:91], 0
	v_mov_b64_e32 v[92:93], 0
	v_mov_b64_e32 v[94:95], 0
	v_mov_b64_e32 v[96:97], 0
	v_mov_b64_e32 v[98:99], 0
	v_mov_b64_e32 v[100:101], 0
	v_mov_b64_e32 v[102:103], 0
	v_mov_b64_e32 v[104:105], 0
	v_mov_b64_e32 v[106:107], 0
	v_mov_b64_e32 v[108:109], 0
	v_mov_b64_e32 v[110:111], 0
	v_mov_b64_e32 v[112:113], 0
	v_mov_b64_e32 v[114:115], 0
	v_mov_b64_e32 v[116:117], 0
	v_mov_b64_e32 v[118:119], 0
	v_mov_b64_e32 v[120:121], 0
	v_mov_b64_e32 v[122:123], 0
	v_mov_b64_e32 v[124:125], 0
	v_mov_b64_e32 v[126:127], 0

; template <class Epi, class Sched, bool ALIGN_EPI = false, bool SP2 = false>
; __device__ __forceinline__ void gemm_phase(LAS unsigned char* lds, const Gemm g, const Sched S, const Epi E) {
;     ...
;         const bool has_next = S.next(ui + 1, nxt);
;         const char* nA = has_next ? (const char*)g.A + (size_t)nxt.pm * tstep : cA; const char* nB = has_next ? (const char*)g.Bt + (size_t)nxt.pn * tstep : cB;
;     ...
; #pragma unroll
;         for (int a = 0; a < 2; ++a)
; #pragma unroll
;             for (int b = 0; b < 2; ++b)
; #pragma unroll
;                 for (int m = 0; m < 4; ++m)
; #pragma unroll
;                     for (int n = 0; n < 2; ++n) acc[a][b][m][n] = (f32x4){0.f, 0.f, 0.f, 0.f};
;         cur = nxt; cA = nA; cB = nB; ++ui;
.LBB0_281:
	s_ashr_i32 s27, s26, 31
	s_lshl_b64 s[34:35], s[26:27], 20
	s_add_u32 s34, s12, s34
	s_addc_u32 s35, s13, s35
	s_and_b64 s[36:37], s[2:3], exec
	s_cselect_b32 s27, s35, s43
	s_cselect_b32 s39, s34, s42
	s_ashr_i32 s25, s24, 31
	s_lshl_b64 s[36:37], s[24:25], 20
	v_readlane_b32 s48, v254, 18
	v_readlane_b32 s49, v254, 19
	s_add_u32 s36, s48, s36
	s_addc_u32 s37, s49, s37
	s_and_b64 s[48:49], s[2:3], exec
	s_cselect_b32 s25, s37, s41
	s_cselect_b32 s48, s36, s40
	v_lshl_add_u32 v216, s4, 8, v218
	s_add_u32 s4, s42, 0x80080
	s_addc_u32 s5, s43, 0
	v_ashrrev_i32_e32 v217, 31, v216
	s_add_u32 s49, s40, 0x100
	v_mov_b32_e32 v0, 0
	v_lshl_add_u64 v[128:129], v[216:217], 2, s[18:19]
	s_addc_u32 s50, s41, 0
	s_mov_b32 s51, -2
	v_mov_b64_e32 v[0:1], 0
	v_mov_b64_e32 v[2:3], 0
	v_mov_b64_e32 v[4:5], 0
	v_mov_b64_e32 v[6:7], 0
	v_mov_b64_e32 v[8:9], 0
	v_mov_b64_e32 v[10:11], 0
	v_mov_b64_e32 v[12:13], 0
	v_mov_b64_e32 v[14:15], 0
	v_mov_b64_e32 v[16:17], 0
	v_mov_b64_e32 v[18:19], 0
	v_mov_b64_e32 v[20:21], 0
	v_mov_b64_e32 v[22:23], 0
	v_mov_b64_e32 v[24:25], 0
	v_mov_b64_e32 v[26:27], 0
	v_mov_b64_e32 v[28:29], 0
	v_mov_b64_e32 v[30:31], 0
	v_mov_b64_e32 v[32:33], 0
	v_mov_b64_e32 v[34:35], 0
	v_mov_b64_e32 v[36:37], 0
	v_mov_b64_e32 v[38:39], 0
	v_mov_b64_e32 v[40:41], 0
	v_mov_b64_e32 v[42:43], 0
	v_mov_b64_e32 v[44:45], 0
	v_mov_b64_e32 v[46:47], 0
	v_mov_b64_e32 v[48:49], 0
	v_mov_b64_e32 v[50:51], 0
	v_mov_b64_e32 v[52:53], 0
	v_mov_b64_e32 v[54:55], 0
	v_mov_b64_e32 v[56:57], 0
	v_mov_b64_e32 v[58:59], 0
	v_mov_b64_e32 v[60:61], 0
	v_mov_b64_e32 v[62:63], 0
	v_mov_b64_e32 v[64:65], 0
	v_mov_b64_e32 v[66:67], 0
	v_mov_b64_e32 v[68:69], 0
	v_mov_b64_e32 v[70:71], 0
	v_mov_b64_e32 v[72:73], 0
	v_mov_b64_e32 v[74:75], 0
	v_mov_b64_e32 v[76:77], 0
	v_mov_b64_e32 v[78:79], 0
	v_mov_b64_e32 v[80:81], 0
	v_mov_b64_e32 v[82:83], 0
	v_mov_b64_e32 v[84:85], 0
	v_mov_b64_e32 v[86:87], 0
	v_mov_b64_e32 v[88:89], 0
	v_mov_b64_e32 v[90:91], 0
	v_mov_b64_e32 v[92:93], 0
	v_mov_b64_e32 v[94:95], 0
	v_mov_b64_e32 v[96:97], 0
	v_mov_b64_e32 v[98:99], 0
	v_mov_b64_e32 v[100:101], 0
	v_mov_b64_e32 v[102:103], 0
	v_mov_b64_e32 v[104:105], 0
	v_mov_b64_e32 v[106:107], 0
	v_mov_b64_e32 v[108:109], 0
	v_mov_b64_e32 v[110:111], 0
	v_mov_b64_e32 v[112:113], 0
	v_mov_b64_e32 v[114:115], 0
	v_mov_b64_e32 v[116:117], 0
	v_mov_b64_e32 v[118:119], 0
	v_mov_b64_e32 v[120:121], 0
	v_mov_b64_e32 v[122:123], 0
	v_mov_b64_e32 v[124:125], 0
	v_mov_b64_e32 v[126:127], 0
	s_branch .LBB0_283

; template <class Epi, class Sched, bool ALIGN_EPI = false, bool SP2 = false>
; __device__ __forceinline__ void gemm_phase(LAS unsigned char* lds, const Gemm g, const Sched S, const Epi E) {
;     ...
;         const bool has_next = S.next(ui + 1, nxt);
;         const char* nA = has_next ? (const char*)g.A + (size_t)nxt.pm * tstep : cA; const char* nB = has_next ? (const char*)g.Bt + (size_t)nxt.pn * tstep : cB;
;     ...
; #pragma unroll
;         for (int a = 0; a < 2; ++a)
; #pragma unroll
;             for (int b = 0; b < 2; ++b)
; #pragma unroll
;                 for (int m = 0; m < 4; ++m)
; #pragma unroll
;                     for (int n = 0; n < 2; ++n) acc[a][b][m][n] = (f32x4){0.f, 0.f, 0.f, 0.f};
;         cur = nxt; cA = nA; cB = nB; ++ui;
.LBB0_477:
	s_ashr_i32 s27, s26, 31
	s_lshl_b64 s[34:35], s[26:27], 19
	s_add_u32 s34, s4, s34
	s_addc_u32 s35, s5, s35
	s_and_b64 s[36:37], s[2:3], exec
	s_cselect_b32 s27, s35, s41
	s_cselect_b32 s48, s34, s40
	s_ashr_i32 s25, s24, 31
	s_lshl_b64 s[36:37], s[24:25], 19
	v_readlane_b32 s44, v254, 22
	v_readlane_b32 s45, v254, 23
	s_add_u32 s36, s44, s36
	s_addc_u32 s37, s45, s37
	s_and_b64 s[44:45], s[2:3], exec
	s_cselect_b32 s25, s37, s43
	s_cselect_b32 s49, s36, s42
	s_add_u32 s40, s40, 0x40080
	s_addc_u32 s41, s41, 0
	s_add_u32 s50, s42, 0x100
	v_mov_b32_e32 v0, 0
	s_addc_u32 s51, s43, 0
	s_mov_b32 s52, -2
	v_mov_b64_e32 v[0:1], 0
	v_mov_b64_e32 v[2:3], 0
	v_mov_b64_e32 v[4:5], 0
	v_mov_b64_e32 v[6:7], 0
	v_mov_b64_e32 v[8:9], 0
	v_mov_b64_e32 v[10:11], 0
	v_mov_b64_e32 v[12:13], 0
	v_mov_b64_e32 v[14:15], 0
	v_mov_b64_e32 v[16:17], 0
	v_mov_b64_e32 v[18:19], 0
	v_mov_b64_e32 v[20:21], 0
	v_mov_b64_e32 v[22:23], 0
	v_mov_b64_e32 v[24:25], 0
	v_mov_b64_e32 v[26:27], 0
	v_mov_b64_e32 v[28:29], 0
	v_mov_b64_e32 v[30:31], 0
	v_mov_b64_e32 v[32:33], 0
	v_mov_b64_e32 v[34:35], 0
	v_mov_b64_e32 v[36:37], 0
	v_mov_b64_e32 v[38:39], 0
	v_mov_b64_e32 v[40:41], 0
	v_mov_b64_e32 v[42:43], 0
	v_mov_b64_e32 v[44:45], 0
	v_mov_b64_e32 v[46:47], 0
	v_mov_b64_e32 v[48:49], 0
	v_mov_b64_e32 v[50:51], 0
	v_mov_b64_e32 v[52:53], 0
	v_mov_b64_e32 v[54:55], 0
	v_mov_b64_e32 v[56:57], 0
	v_mov_b64_e32 v[58:59], 0
	v_mov_b64_e32 v[60:61], 0
	v_mov_b64_e32 v[62:63], 0
	v_mov_b64_e32 v[64:65], 0
	v_mov_b64_e32 v[66:67], 0
	v_mov_b64_e32 v[68:69], 0
	v_mov_b64_e32 v[70:71], 0
	v_mov_b64_e32 v[72:73], 0
	v_mov_b64_e32 v[74:75], 0
	v_mov_b64_e32 v[76:77], 0
	v_mov_b64_e32 v[78:79], 0
	v_mov_b64_e32 v[80:81], 0
	v_mov_b64_e32 v[82:83], 0
	v_mov_b64_e32 v[84:85], 0
	v_mov_b64_e32 v[86:87], 0
	v_mov_b64_e32 v[88:89], 0
	v_mov_b64_e32 v[90:91], 0
	v_mov_b64_e32 v[92:93], 0
	v_mov_b64_e32 v[94:95], 0
	v_mov_b64_e32 v[96:97], 0
	v_mov_b64_e32 v[98:99], 0
	v_mov_b64_e32 v[100:101], 0
	v_mov_b64_e32 v[102:103], 0
	v_mov_b64_e32 v[104:105], 0
	v_mov_b64_e32 v[106:107], 0
	v_mov_b64_e32 v[108:109], 0
	v_mov_b64_e32 v[110:111], 0
	v_mov_b64_e32 v[112:113], 0
	v_mov_b64_e32 v[114:115], 0
	v_mov_b64_e32 v[116:117], 0
	v_mov_b64_e32 v[118:119], 0
	v_mov_b64_e32 v[120:121], 0
	v_mov_b64_e32 v[122:123], 0
	v_mov_b64_e32 v[124:125], 0
	v_mov_b64_e32 v[126:127], 0

; template <class Epi, class Sched, bool ALIGN_EPI = false, bool SP2 = false>
; __device__ __forceinline__ void gemm_phase(LAS unsigned char* lds, const Gemm g, const Sched S, const Epi E) {
;     ...
;         const bool has_next = S.next(ui + 1, nxt);
;         const char* nA = has_next ? (const char*)g.A + (size_t)nxt.pm * tstep : cA; const char* nB = has_next ? (const char*)g.Bt + (size_t)nxt.pn * tstep : cB;
;     ...
; #pragma unroll
;         for (int a = 0; a < 2; ++a)
; #pragma unroll
;             for (int b = 0; b < 2; ++b)
; #pragma unroll
;                 for (int m = 0; m < 4; ++m)
; #pragma unroll
;                     for (int n = 0; n < 2; ++n) acc[a][b][m][n] = (f32x4){0.f, 0.f, 0.f, 0.f};
;         cur = nxt; cA = nA; cB = nB; ++ui;
.LBB0_558:
	s_ashr_i32 s27, s26, 31
	s_lshl_b64 s[34:35], s[26:27], 20
	s_add_u32 s34, s18, s34
	s_addc_u32 s35, s19, s35
	s_and_b64 s[36:37], s[4:5], exec
	s_cselect_b32 s27, s35, s43
	s_cselect_b32 s39, s34, s42
	s_ashr_i32 s25, s24, 31
	s_lshl_b64 s[36:37], s[24:25], 20
	v_readlane_b32 s46, v254, 20
	v_readlane_b32 s47, v254, 21
	s_add_u32 s36, s46, s36
	s_addc_u32 s37, s47, s37
	s_and_b64 s[46:47], s[4:5], exec
	s_cselect_b32 s25, s37, s45
	s_cselect_b32 s51, s36, s44
	s_add_u32 s42, s42, 0x80080
	s_addc_u32 s43, s43, 0
	s_add_u32 s52, s44, 0x100
	v_mov_b32_e32 v0, 0
	s_addc_u32 s53, s45, 0
	s_mov_b32 s54, -2
	s_waitcnt lgkmcnt(0)
	v_mov_b64_e32 v[0:1], 0
	v_mov_b64_e32 v[2:3], 0
	v_mov_b64_e32 v[4:5], 0
	v_mov_b64_e32 v[6:7], 0
	v_mov_b64_e32 v[8:9], 0
	v_mov_b64_e32 v[10:11], 0
	v_mov_b64_e32 v[12:13], 0
	v_mov_b64_e32 v[14:15], 0
	v_mov_b64_e32 v[16:17], 0
	v_mov_b64_e32 v[18:19], 0
	v_mov_b64_e32 v[20:21], 0
	v_mov_b64_e32 v[22:23], 0
	v_mov_b64_e32 v[24:25], 0
	v_mov_b64_e32 v[26:27], 0
	v_mov_b64_e32 v[28:29], 0
	v_mov_b64_e32 v[30:31], 0
	v_mov_b64_e32 v[32:33], 0
	v_mov_b64_e32 v[34:35], 0
	v_mov_b64_e32 v[36:37], 0
	v_mov_b64_e32 v[38:39], 0
	v_mov_b64_e32 v[40:41], 0
	v_mov_b64_e32 v[42:43], 0
	v_mov_b64_e32 v[44:45], 0
	v_mov_b64_e32 v[46:47], 0
	v_mov_b64_e32 v[48:49], 0
	v_mov_b64_e32 v[50:51], 0
	v_mov_b64_e32 v[52:53], 0
	v_mov_b64_e32 v[54:55], 0
	v_mov_b64_e32 v[56:57], 0
	v_mov_b64_e32 v[58:59], 0
	v_mov_b64_e32 v[60:61], 0
	v_mov_b64_e32 v[62:63], 0
	v_mov_b64_e32 v[64:65], 0
	v_mov_b64_e32 v[66:67], 0
	v_mov_b64_e32 v[68:69], 0
	v_mov_b64_e32 v[70:71], 0
	v_mov_b64_e32 v[72:73], 0
	v_mov_b64_e32 v[74:75], 0
	v_mov_b64_e32 v[76:77], 0
	v_mov_b64_e32 v[78:79], 0
	v_mov_b64_e32 v[80:81], 0
	v_mov_b64_e32 v[82:83], 0
	v_mov_b64_e32 v[84:85], 0
	v_mov_b64_e32 v[86:87], 0
	v_mov_b64_e32 v[88:89], 0
	v_mov_b64_e32 v[90:91], 0
	v_mov_b64_e32 v[92:93], 0
	v_mov_b64_e32 v[94:95], 0
	v_mov_b64_e32 v[96:97], 0
	v_mov_b64_e32 v[98:99], 0
	v_mov_b64_e32 v[100:101], 0
	v_mov_b64_e32 v[102:103], 0
	v_mov_b64_e32 v[104:105], 0
	v_mov_b64_e32 v[106:107], 0
	v_mov_b64_e32 v[108:109], 0
	v_mov_b64_e32 v[110:111], 0
	v_mov_b64_e32 v[112:113], 0
	v_mov_b64_e32 v[114:115], 0
	v_mov_b64_e32 v[116:117], 0
	v_mov_b64_e32 v[118:119], 0
	v_mov_b64_e32 v[120:121], 0
	v_mov_b64_e32 v[122:123], 0
	v_mov_b64_e32 v[124:125], 0
	v_mov_b64_e32 v[126:127], 0

; template <class Epi, class Sched, bool ALIGN_EPI = false, bool SP2 = false>
; __device__ __forceinline__ void gemm_phase(LAS unsigned char* lds, const Gemm g, const Sched S, const Epi E) {
;     ...
;         const bool has_next = S.next(ui + 1, nxt);
;         const char* nA = has_next ? (const char*)g.A + (size_t)nxt.pm * tstep : cA; const char* nB = has_next ? (const char*)g.Bt + (size_t)nxt.pn * tstep : cB;
;     ...
; #pragma unroll
;         for (int a = 0; a < 2; ++a)
; #pragma unroll
;             for (int b = 0; b < 2; ++b)
; #pragma unroll
;                 for (int m = 0; m < 4; ++m)
; #pragma unroll
;                     for (int n = 0; n < 2; ++n) acc[a][b][m][n] = (f32x4){0.f, 0.f, 0.f, 0.f};
;         cur = nxt; cA = nA; cB = nB; ++ui;
.LBB0_645:
	s_ashr_i32 s25, s24, 31
	s_lshl_b64 s[26:27], s[24:25], 20
	s_add_u32 s26, s12, s26
	s_addc_u32 s27, s13, s27
	s_and_b64 s[34:35], s[2:3], exec
	s_cselect_b32 s25, s27, s41
	s_cselect_b32 s51, s26, s40
	s_ashr_i32 s23, s22, 31
	s_lshl_b64 s[34:35], s[22:23], 20
	s_add_u32 s34, s8, s34
	s_addc_u32 s35, s9, s35
	s_and_b64 s[52:53], s[2:3], exec
	s_cselect_b32 s23, s35, s39
	s_cselect_b32 s52, s34, s38
	v_lshl_add_u32 v144, s36, 8, v148
	s_add_u32 s36, s40, 0x80080
	s_addc_u32 s37, s41, 0
	v_ashrrev_i32_e32 v145, 31, v144
	s_add_u32 s53, s38, 0x100
	v_mov_b32_e32 v0, 0
	v_lshl_add_u64 v[146:147], v[144:145], 2, s[6:7]
	s_addc_u32 s54, s39, 0
	s_mov_b32 s55, -2
	v_mov_b64_e32 v[0:1], 0
	v_mov_b64_e32 v[2:3], 0
	v_mov_b64_e32 v[4:5], 0
	v_mov_b64_e32 v[6:7], 0
	v_mov_b64_e32 v[8:9], 0
	v_mov_b64_e32 v[10:11], 0
	v_mov_b64_e32 v[12:13], 0
	v_mov_b64_e32 v[14:15], 0
	v_mov_b64_e32 v[16:17], 0
	v_mov_b64_e32 v[18:19], 0
	v_mov_b64_e32 v[20:21], 0
	v_mov_b64_e32 v[22:23], 0
	v_mov_b64_e32 v[24:25], 0
	v_mov_b64_e32 v[26:27], 0
	v_mov_b64_e32 v[28:29], 0
	v_mov_b64_e32 v[30:31], 0
	v_mov_b64_e32 v[32:33], 0
	v_mov_b64_e32 v[34:35], 0
	v_mov_b64_e32 v[36:37], 0
	v_mov_b64_e32 v[38:39], 0
	v_mov_b64_e32 v[40:41], 0
	v_mov_b64_e32 v[42:43], 0
	v_mov_b64_e32 v[44:45], 0
	v_mov_b64_e32 v[46:47], 0
	v_mov_b64_e32 v[48:49], 0
	v_mov_b64_e32 v[50:51], 0
	v_mov_b64_e32 v[52:53], 0
	v_mov_b64_e32 v[54:55], 0
	v_mov_b64_e32 v[56:57], 0
	v_mov_b64_e32 v[58:59], 0
	v_mov_b64_e32 v[60:61], 0
	v_mov_b64_e32 v[62:63], 0
	v_mov_b64_e32 v[64:65], 0
	v_mov_b64_e32 v[66:67], 0
	v_mov_b64_e32 v[68:69], 0
	v_mov_b64_e32 v[70:71], 0
	v_mov_b64_e32 v[72:73], 0
	v_mov_b64_e32 v[74:75], 0
	v_mov_b64_e32 v[76:77], 0
	v_mov_b64_e32 v[78:79], 0
	v_mov_b64_e32 v[80:81], 0
	v_mov_b64_e32 v[82:83], 0
	v_mov_b64_e32 v[84:85], 0
	v_mov_b64_e32 v[86:87], 0
	v_mov_b64_e32 v[88:89], 0
	v_mov_b64_e32 v[90:91], 0
	v_mov_b64_e32 v[92:93], 0
	v_mov_b64_e32 v[94:95], 0
	v_mov_b64_e32 v[96:97], 0
	v_mov_b64_e32 v[98:99], 0
	v_mov_b64_e32 v[100:101], 0
	v_mov_b64_e32 v[102:103], 0
	v_mov_b64_e32 v[104:105], 0
	v_mov_b64_e32 v[106:107], 0
	v_mov_b64_e32 v[108:109], 0
	v_mov_b64_e32 v[110:111], 0
	v_mov_b64_e32 v[112:113], 0
	v_mov_b64_e32 v[114:115], 0
	v_mov_b64_e32 v[116:117], 0
	v_mov_b64_e32 v[118:119], 0
	v_mov_b64_e32 v[120:121], 0
	v_mov_b64_e32 v[122:123], 0
	v_mov_b64_e32 v[124:125], 0
	v_mov_b64_e32 v[126:127], 0
	s_branch .LBB0_647

; template <class Epi, class Sched, bool ALIGN_EPI = false, bool SP2 = false>
; __device__ __forceinline__ void gemm_phase(LAS unsigned char* lds, const Gemm g, const Sched S, const Epi E) {
;     ...
; #pragma unroll
;         for (int a = 0; a < 2; ++a)
; #pragma unroll
;             for (int b = 0; b < 2; ++b)
; #pragma unroll
;                 for (int m = 0; m < 4; ++m)
; #pragma unroll
;                     for (int n = 0; n < 2; ++n) acc[a][b][m][n] = (f32x4){0.f, 0.f, 0.f, 0.f};
;         cur = nxt; cA = nA; cB = nB; ++ui;
.LBB0_732:
	s_add_u32 s34, s34, 0x158080
	s_addc_u32 s35, s35, 0
	s_add_u32 s50, s36, 0x100
	v_mov_b32_e32 v0, 0
	s_addc_u32 s51, s37, 0
	s_mov_b32 s52, -2
	s_waitcnt lgkmcnt(0)
	v_mov_b64_e32 v[0:1], 0
	v_mov_b64_e32 v[2:3], 0
	v_mov_b64_e32 v[4:5], 0
	v_mov_b64_e32 v[6:7], 0
	v_mov_b64_e32 v[8:9], 0
	v_mov_b64_e32 v[10:11], 0
	v_mov_b64_e32 v[12:13], 0
	v_mov_b64_e32 v[14:15], 0
	v_mov_b64_e32 v[16:17], 0
	v_mov_b64_e32 v[18:19], 0
	v_mov_b64_e32 v[20:21], 0
	v_mov_b64_e32 v[22:23], 0
	v_mov_b64_e32 v[24:25], 0
	v_mov_b64_e32 v[26:27], 0
	v_mov_b64_e32 v[28:29], 0
	v_mov_b64_e32 v[30:31], 0
	v_mov_b64_e32 v[32:33], 0
	v_mov_b64_e32 v[34:35], 0
	v_mov_b64_e32 v[36:37], 0
	v_mov_b64_e32 v[38:39], 0
	v_mov_b64_e32 v[40:41], 0
	v_mov_b64_e32 v[42:43], 0
	v_mov_b64_e32 v[44:45], 0
	v_mov_b64_e32 v[46:47], 0
	v_mov_b64_e32 v[48:49], 0
	v_mov_b64_e32 v[50:51], 0
	v_mov_b64_e32 v[52:53], 0
	v_mov_b64_e32 v[54:55], 0
	v_mov_b64_e32 v[56:57], 0
	v_mov_b64_e32 v[58:59], 0
	v_mov_b64_e32 v[60:61], 0
	v_mov_b64_e32 v[62:63], 0
	v_mov_b64_e32 v[64:65], 0
	v_mov_b64_e32 v[66:67], 0
	v_mov_b64_e32 v[68:69], 0
	v_mov_b64_e32 v[70:71], 0
	v_mov_b64_e32 v[72:73], 0
	v_mov_b64_e32 v[74:75], 0
	v_mov_b64_e32 v[76:77], 0
	v_mov_b64_e32 v[78:79], 0
	v_mov_b64_e32 v[80:81], 0
	v_mov_b64_e32 v[82:83], 0
	v_mov_b64_e32 v[84:85], 0
	v_mov_b64_e32 v[86:87], 0
	v_mov_b64_e32 v[88:89], 0
	v_mov_b64_e32 v[90:91], 0
	v_mov_b64_e32 v[92:93], 0
	v_mov_b64_e32 v[94:95], 0
	v_mov_b64_e32 v[96:97], 0
	v_mov_b64_e32 v[98:99], 0
	v_mov_b64_e32 v[100:101], 0
	v_mov_b64_e32 v[102:103], 0
	v_mov_b64_e32 v[104:105], 0
	v_mov_b64_e32 v[106:107], 0
	v_mov_b64_e32 v[108:109], 0
	v_mov_b64_e32 v[110:111], 0
	v_mov_b64_e32 v[112:113], 0
	v_mov_b64_e32 v[114:115], 0
	v_mov_b64_e32 v[116:117], 0
	v_mov_b64_e32 v[118:119], 0
	v_mov_b64_e32 v[120:121], 0
	v_mov_b64_e32 v[122:123], 0
	v_mov_b64_e32 v[124:125], 0
	v_mov_b64_e32 v[126:127], 0

; template <class Epi, class Sched, bool ALIGN_EPI = false, bool SP2 = false>
; __device__ __forceinline__ void gemm_phase(LAS unsigned char* lds, const Gemm g, const Sched S, const Epi E) {
;     ...
; #pragma unroll
;         for (int a = 0; a < 2; ++a)
; #pragma unroll
;             for (int b = 0; b < 2; ++b)
; #pragma unroll
;                 for (int m = 0; m < 4; ++m)
; #pragma unroll
;                     for (int n = 0; n < 2; ++n) acc[a][b][m][n] = (f32x4){0.f, 0.f, 0.f, 0.f};
;         cur = nxt; cA = nA; cB = nB; ++ui;
;     __device__ __forceinline__ void prefetch(const Unit& u, int wr, int fr, Pre& pre) const {
; #pragma unroll
;         for (int ai = 0; ai < 2; ++ai)
; #pragma unroll
;             for (int m = 0; m < 4; ++m) pre.v[ai][m] = ssq[u.pm * 256 + ai * 128 + wr * 64 + m * 16 + fr];
.LBB0_995:
	s_ashr_i32 s35, s34, 31
	s_lshl_b64 s[36:37], s[34:35], 20
	s_add_u32 s36, s12, s36
	s_addc_u32 s37, s13, s37
	s_and_b64 s[38:39], s[2:3], exec
	s_cselect_b32 s35, s37, s45
	s_cselect_b32 s52, s36, s44
	s_ashr_i32 s27, s26, 31
	s_lshl_b64 s[38:39], s[26:27], 20
	v_readlane_b32 s54, v254, 24
	v_readlane_b32 s55, v254, 25
	s_add_u32 s38, s54, s38
	s_addc_u32 s39, s55, s39
	s_and_b64 s[54:55], s[2:3], exec
	s_cselect_b32 s53, s39, s43
	s_cselect_b32 s54, s38, s42
	s_lshl_b32 s27, s4, 8
	v_add_u32_e32 v0, s27, v213
	v_ashrrev_i32_e32 v1, 31, v0
	v_lshl_add_u64 v[128:129], v[0:1], 2, s[14:15]
	v_or_b32_e32 v0, 16, v213
	v_add_u32_e32 v0, s27, v0
	v_ashrrev_i32_e32 v1, 31, v0
	v_lshl_add_u64 v[130:131], v[0:1], 2, s[14:15]
	v_or_b32_e32 v0, 32, v213
	v_add_u32_e32 v0, s27, v0
	v_ashrrev_i32_e32 v1, 31, v0
	v_lshl_add_u64 v[132:133], v[0:1], 2, s[14:15]
	v_or_b32_e32 v0, 48, v213
	v_add_u32_e32 v0, s27, v0
	v_ashrrev_i32_e32 v1, 31, v0
	v_lshl_add_u64 v[134:135], v[0:1], 2, s[14:15]
	v_add_u32_e32 v0, 0x80, v213
	v_add_u32_e32 v0, s27, v0
	v_ashrrev_i32_e32 v1, 31, v0
	v_lshl_add_u64 v[136:137], v[0:1], 2, s[14:15]
	v_add_u32_e32 v0, 0x90, v213
	v_add_u32_e32 v0, s27, v0
	v_ashrrev_i32_e32 v1, 31, v0
	v_lshl_add_u64 v[138:139], v[0:1], 2, s[14:15]
	v_add_u32_e32 v0, s27, v215
	v_ashrrev_i32_e32 v1, 31, v0
	v_lshl_add_u64 v[140:141], v[0:1], 2, s[14:15]
	v_add_u32_e32 v0, s27, v216
	s_add_u32 s4, s44, 0x80080
	v_ashrrev_i32_e32 v1, 31, v0
	s_addc_u32 s5, s45, 0
	v_lshl_add_u64 v[142:143], v[0:1], 2, s[14:15]
	s_add_u32 s55, s42, 0x100
	v_mov_b32_e32 v0, 0
	s_addc_u32 s56, s43, 0
	s_mov_b32 s57, -2
	v_mov_b64_e32 v[0:1], 0
	v_mov_b64_e32 v[2:3], 0
	v_mov_b64_e32 v[4:5], 0
	v_mov_b64_e32 v[6:7], 0
	v_mov_b64_e32 v[8:9], 0
	v_mov_b64_e32 v[10:11], 0
	v_mov_b64_e32 v[12:13], 0
	v_mov_b64_e32 v[14:15], 0
	v_mov_b64_e32 v[16:17], 0
	v_mov_b64_e32 v[18:19], 0
	v_mov_b64_e32 v[20:21], 0
	v_mov_b64_e32 v[22:23], 0
	v_mov_b64_e32 v[24:25], 0
	v_mov_b64_e32 v[26:27], 0
	v_mov_b64_e32 v[28:29], 0
	v_mov_b64_e32 v[30:31], 0
	v_mov_b64_e32 v[32:33], 0
	v_mov_b64_e32 v[34:35], 0
	v_mov_b64_e32 v[36:37], 0
	v_mov_b64_e32 v[38:39], 0
	v_mov_b64_e32 v[40:41], 0
	v_mov_b64_e32 v[42:43], 0
	v_mov_b64_e32 v[44:45], 0
	v_mov_b64_e32 v[46:47], 0
	v_mov_b64_e32 v[48:49], 0
	v_mov_b64_e32 v[50:51], 0
	v_mov_b64_e32 v[52:53], 0
	v_mov_b64_e32 v[54:55], 0
	v_mov_b64_e32 v[56:57], 0
	v_mov_b64_e32 v[58:59], 0
	v_mov_b64_e32 v[60:61], 0
	v_mov_b64_e32 v[62:63], 0
	v_mov_b64_e32 v[64:65], 0
	v_mov_b64_e32 v[66:67], 0
	v_mov_b64_e32 v[68:69], 0
	v_mov_b64_e32 v[70:71], 0
	v_mov_b64_e32 v[72:73], 0
	v_mov_b64_e32 v[74:75], 0
	v_mov_b64_e32 v[76:77], 0
	v_mov_b64_e32 v[78:79], 0
	v_mov_b64_e32 v[80:81], 0
	v_mov_b64_e32 v[82:83], 0
	v_mov_b64_e32 v[84:85], 0
	v_mov_b64_e32 v[86:87], 0
	v_mov_b64_e32 v[88:89], 0
	v_mov_b64_e32 v[90:91], 0
	v_mov_b64_e32 v[92:93], 0
	v_mov_b64_e32 v[94:95], 0
	v_mov_b64_e32 v[96:97], 0
	v_mov_b64_e32 v[98:99], 0
	v_mov_b64_e32 v[100:101], 0
	v_mov_b64_e32 v[102:103], 0
	v_mov_b64_e32 v[104:105], 0
	v_mov_b64_e32 v[106:107], 0
	v_mov_b64_e32 v[108:109], 0
	v_mov_b64_e32 v[110:111], 0
	v_mov_b64_e32 v[112:113], 0
	v_mov_b64_e32 v[114:115], 0
	v_mov_b64_e32 v[116:117], 0
	v_mov_b64_e32 v[118:119], 0
	v_mov_b64_e32 v[120:121], 0
	v_mov_b64_e32 v[122:123], 0
	v_mov_b64_e32 v[124:125], 0
	v_mov_b64_e32 v[126:127], 0
	s_branch .LBB0_997

; template <class Epi, class Sched, bool ALIGN_EPI = false, bool SP2 = false>
; __device__ __forceinline__ void gemm_phase(LAS unsigned char* lds, const Gemm g, const Sched S, const Epi E) {
;     ...
;         const bool has_next = S.next(ui + 1, nxt);
;         const char* nA = has_next ? (const char*)g.A + (size_t)nxt.pm * tstep : cA; const char* nB = has_next ? (const char*)g.Bt + (size_t)nxt.pn * tstep : cB;
;     ...
; #pragma unroll
;         for (int a = 0; a < 2; ++a)
; #pragma unroll
;             for (int b = 0; b < 2; ++b)
; #pragma unroll
;                 for (int m = 0; m < 4; ++m)
; #pragma unroll
;                     for (int n = 0; n < 2; ++n) acc[a][b][m][n] = (f32x4){0.f, 0.f, 0.f, 0.f};
;         cur = nxt; cA = nA; cB = nB; ++ui;
.LBB0_1200:
	s_ashr_i32 s27, s26, 31
	s_lshl_b64 s[34:35], s[26:27], 20
	s_add_u32 s34, s18, s34
	s_addc_u32 s35, s19, s35
	s_and_b64 s[36:37], s[4:5], exec
	s_cselect_b32 s27, s35, s43
	s_cselect_b32 s39, s34, s42
	s_ashr_i32 s25, s24, 31
	s_lshl_b64 s[36:37], s[24:25], 20
	s_add_u32 s36, s60, s36
	s_addc_u32 s37, s61, s37
	s_and_b64 s[46:47], s[4:5], exec
	s_cselect_b32 s25, s37, s45
	s_cselect_b32 s51, s36, s44
	s_add_u32 s42, s42, 0x80080
	s_addc_u32 s43, s43, 0
	s_add_u32 s52, s44, 0x100
	v_mov_b32_e32 v0, 0
	s_addc_u32 s53, s45, 0
	s_mov_b32 s54, -2
	s_waitcnt lgkmcnt(0)
	v_mov_b64_e32 v[0:1], 0
	v_mov_b64_e32 v[2:3], 0
	v_mov_b64_e32 v[4:5], 0
	v_mov_b64_e32 v[6:7], 0
	v_mov_b64_e32 v[8:9], 0
	v_mov_b64_e32 v[10:11], 0
	v_mov_b64_e32 v[12:13], 0
	v_mov_b64_e32 v[14:15], 0
	v_mov_b64_e32 v[16:17], 0
	v_mov_b64_e32 v[18:19], 0
	v_mov_b64_e32 v[20:21], 0
	v_mov_b64_e32 v[22:23], 0
	v_mov_b64_e32 v[24:25], 0
	v_mov_b64_e32 v[26:27], 0
	v_mov_b64_e32 v[28:29], 0
	v_mov_b64_e32 v[30:31], 0
	v_mov_b64_e32 v[32:33], 0
	v_mov_b64_e32 v[34:35], 0
	v_mov_b64_e32 v[36:37], 0
	v_mov_b64_e32 v[38:39], 0
	v_mov_b64_e32 v[40:41], 0
	v_mov_b64_e32 v[42:43], 0
	v_mov_b64_e32 v[44:45], 0
	v_mov_b64_e32 v[46:47], 0
	v_mov_b64_e32 v[48:49], 0
	v_mov_b64_e32 v[50:51], 0
	v_mov_b64_e32 v[52:53], 0
	v_mov_b64_e32 v[54:55], 0
	v_mov_b64_e32 v[56:57], 0
	v_mov_b64_e32 v[58:59], 0
	v_mov_b64_e32 v[60:61], 0
	v_mov_b64_e32 v[62:63], 0
	v_mov_b64_e32 v[64:65], 0
	v_mov_b64_e32 v[66:67], 0
	v_mov_b64_e32 v[68:69], 0
	v_mov_b64_e32 v[70:71], 0
	v_mov_b64_e32 v[72:73], 0
	v_mov_b64_e32 v[74:75], 0
	v_mov_b64_e32 v[76:77], 0
	v_mov_b64_e32 v[78:79], 0
	v_mov_b64_e32 v[80:81], 0
	v_mov_b64_e32 v[82:83], 0
	v_mov_b64_e32 v[84:85], 0
	v_mov_b64_e32 v[86:87], 0
	v_mov_b64_e32 v[88:89], 0
	v_mov_b64_e32 v[90:91], 0
	v_mov_b64_e32 v[92:93], 0
	v_mov_b64_e32 v[94:95], 0
	v_mov_b64_e32 v[96:97], 0
	v_mov_b64_e32 v[98:99], 0
	v_mov_b64_e32 v[100:101], 0
	v_mov_b64_e32 v[102:103], 0
	v_mov_b64_e32 v[104:105], 0
	v_mov_b64_e32 v[106:107], 0
	v_mov_b64_e32 v[108:109], 0
	v_mov_b64_e32 v[110:111], 0
	v_mov_b64_e32 v[112:113], 0
	v_mov_b64_e32 v[114:115], 0
	v_mov_b64_e32 v[116:117], 0
	v_mov_b64_e32 v[118:119], 0
	v_mov_b64_e32 v[120:121], 0
	v_mov_b64_e32 v[122:123], 0
	v_mov_b64_e32 v[124:125], 0
	v_mov_b64_e32 v[126:127], 0

; template <class Epi, class Sched, bool ALIGN_EPI = false, bool SP2 = false>
; __device__ __forceinline__ void gemm_phase(LAS unsigned char* lds, const Gemm g, const Sched S, const Epi E) {
;     ...
;         const bool has_next = S.next(ui + 1, nxt);
;         const char* nA = has_next ? (const char*)g.A + (size_t)nxt.pm * tstep : cA; const char* nB = has_next ? (const char*)g.Bt + (size_t)nxt.pn * tstep : cB;
;     ...
; #pragma unroll
;         for (int a = 0; a < 2; ++a)
; #pragma unroll
;             for (int b = 0; b < 2; ++b)
; #pragma unroll
;                 for (int m = 0; m < 4; ++m)
; #pragma unroll
;                     for (int n = 0; n < 2; ++n) acc[a][b][m][n] = (f32x4){0.f, 0.f, 0.f, 0.f};
;         cur = nxt; cA = nA; cB = nB; ++ui;
.LBB0_1287:
	s_ashr_i32 s23, s22, 31
	s_lshl_b64 s[24:25], s[22:23], 20
	s_add_u32 s24, s12, s24
	s_addc_u32 s25, s13, s25
	s_and_b64 s[26:27], s[2:3], exec
	s_cselect_b32 s23, s25, s39
	s_cselect_b32 s49, s24, s38
	s_ashr_i32 s21, s20, 31
	s_lshl_b64 s[26:27], s[20:21], 20
	s_add_u32 s26, s8, s26
	s_addc_u32 s27, s9, s27
	s_and_b64 s[50:51], s[2:3], exec
	s_cselect_b32 s21, s27, s37
	s_cselect_b32 s50, s26, s36
	v_lshl_add_u32 v144, s34, 8, v148
	s_add_u32 s34, s38, 0x80080
	s_addc_u32 s35, s39, 0
	v_ashrrev_i32_e32 v145, 31, v144
	s_add_u32 s51, s36, 0x100
	v_mov_b32_e32 v0, 0
	v_lshl_add_u64 v[146:147], v[144:145], 2, s[6:7]
	s_addc_u32 s52, s37, 0
	s_mov_b32 s53, -2
	v_mov_b64_e32 v[0:1], 0
	v_mov_b64_e32 v[2:3], 0
	v_mov_b64_e32 v[4:5], 0
	v_mov_b64_e32 v[6:7], 0
	v_mov_b64_e32 v[8:9], 0
	v_mov_b64_e32 v[10:11], 0
	v_mov_b64_e32 v[12:13], 0
	v_mov_b64_e32 v[14:15], 0
	v_mov_b64_e32 v[16:17], 0
	v_mov_b64_e32 v[18:19], 0
	v_mov_b64_e32 v[20:21], 0
	v_mov_b64_e32 v[22:23], 0
	v_mov_b64_e32 v[24:25], 0
	v_mov_b64_e32 v[26:27], 0
	v_mov_b64_e32 v[28:29], 0
	v_mov_b64_e32 v[30:31], 0
	v_mov_b64_e32 v[32:33], 0
	v_mov_b64_e32 v[34:35], 0
	v_mov_b64_e32 v[36:37], 0
	v_mov_b64_e32 v[38:39], 0
	v_mov_b64_e32 v[40:41], 0
	v_mov_b64_e32 v[42:43], 0
	v_mov_b64_e32 v[44:45], 0
	v_mov_b64_e32 v[46:47], 0
	v_mov_b64_e32 v[48:49], 0
	v_mov_b64_e32 v[50:51], 0
	v_mov_b64_e32 v[52:53], 0
	v_mov_b64_e32 v[54:55], 0
	v_mov_b64_e32 v[56:57], 0
	v_mov_b64_e32 v[58:59], 0
	v_mov_b64_e32 v[60:61], 0
	v_mov_b64_e32 v[62:63], 0
	v_mov_b64_e32 v[64:65], 0
	v_mov_b64_e32 v[66:67], 0
	v_mov_b64_e32 v[68:69], 0
	v_mov_b64_e32 v[70:71], 0
	v_mov_b64_e32 v[72:73], 0
	v_mov_b64_e32 v[74:75], 0
	v_mov_b64_e32 v[76:77], 0
	v_mov_b64_e32 v[78:79], 0
	v_mov_b64_e32 v[80:81], 0
	v_mov_b64_e32 v[82:83], 0
	v_mov_b64_e32 v[84:85], 0
	v_mov_b64_e32 v[86:87], 0
	v_mov_b64_e32 v[88:89], 0
	v_mov_b64_e32 v[90:91], 0
	v_mov_b64_e32 v[92:93], 0
	v_mov_b64_e32 v[94:95], 0
	v_mov_b64_e32 v[96:97], 0
	v_mov_b64_e32 v[98:99], 0
	v_mov_b64_e32 v[100:101], 0
	v_mov_b64_e32 v[102:103], 0
	v_mov_b64_e32 v[104:105], 0
	v_mov_b64_e32 v[106:107], 0
	v_mov_b64_e32 v[108:109], 0
	v_mov_b64_e32 v[110:111], 0
	v_mov_b64_e32 v[112:113], 0
	v_mov_b64_e32 v[114:115], 0
	v_mov_b64_e32 v[116:117], 0
	v_mov_b64_e32 v[118:119], 0
	v_mov_b64_e32 v[120:121], 0
	v_mov_b64_e32 v[122:123], 0
	v_mov_b64_e32 v[124:125], 0
	v_mov_b64_e32 v[126:127], 0
	s_waitcnt vmcnt(0)
	s_branch .LBB0_1289

; template <class Epi, class Sched, bool ALIGN_EPI = false, bool SP2 = false>
; __device__ __forceinline__ void gemm_phase(LAS unsigned char* lds, const Gemm g, const Sched S, const Epi E) {
;     ...
; #pragma unroll
;         for (int a = 0; a < 2; ++a)
; #pragma unroll
;             for (int b = 0; b < 2; ++b)
; #pragma unroll
;                 for (int m = 0; m < 4; ++m)
; #pragma unroll
;                     for (int n = 0; n < 2; ++n) acc[a][b][m][n] = (f32x4){0.f, 0.f, 0.f, 0.f};
;         cur = nxt; cA = nA; cB = nB; ++ui;
.LBB0_1374:
	s_add_u32 s26, s26, 0x158080
	s_addc_u32 s27, s27, 0
	s_add_u32 s48, s34, 0x100
	v_mov_b32_e32 v0, 0
	s_addc_u32 s49, s35, 0
	s_mov_b32 s50, -2
	s_waitcnt lgkmcnt(0)
	v_mov_b64_e32 v[0:1], 0
	v_mov_b64_e32 v[2:3], 0
	v_mov_b64_e32 v[4:5], 0
	v_mov_b64_e32 v[6:7], 0
	v_mov_b64_e32 v[8:9], 0
	v_mov_b64_e32 v[10:11], 0
	v_mov_b64_e32 v[12:13], 0
	v_mov_b64_e32 v[14:15], 0
	v_mov_b64_e32 v[16:17], 0
	v_mov_b64_e32 v[18:19], 0
	v_mov_b64_e32 v[20:21], 0
	v_mov_b64_e32 v[22:23], 0
	v_mov_b64_e32 v[24:25], 0
	v_mov_b64_e32 v[26:27], 0
	v_mov_b64_e32 v[28:29], 0
	v_mov_b64_e32 v[30:31], 0
	v_mov_b64_e32 v[32:33], 0
	v_mov_b64_e32 v[34:35], 0
	v_mov_b64_e32 v[36:37], 0
	v_mov_b64_e32 v[38:39], 0
	v_mov_b64_e32 v[40:41], 0
	v_mov_b64_e32 v[42:43], 0
	v_mov_b64_e32 v[44:45], 0
	v_mov_b64_e32 v[46:47], 0
	v_mov_b64_e32 v[48:49], 0
	v_mov_b64_e32 v[50:51], 0
	v_mov_b64_e32 v[52:53], 0
	v_mov_b64_e32 v[54:55], 0
	v_mov_b64_e32 v[56:57], 0
	v_mov_b64_e32 v[58:59], 0
	v_mov_b64_e32 v[60:61], 0
	v_mov_b64_e32 v[62:63], 0
	v_mov_b64_e32 v[64:65], 0
	v_mov_b64_e32 v[66:67], 0
	v_mov_b64_e32 v[68:69], 0
	v_mov_b64_e32 v[70:71], 0
	v_mov_b64_e32 v[72:73], 0
	v_mov_b64_e32 v[74:75], 0
	v_mov_b64_e32 v[76:77], 0
	v_mov_b64_e32 v[78:79], 0
	v_mov_b64_e32 v[80:81], 0
	v_mov_b64_e32 v[82:83], 0
	v_mov_b64_e32 v[84:85], 0
	v_mov_b64_e32 v[86:87], 0
	v_mov_b64_e32 v[88:89], 0
	v_mov_b64_e32 v[90:91], 0
	v_mov_b64_e32 v[92:93], 0
	v_mov_b64_e32 v[94:95], 0
	v_mov_b64_e32 v[96:97], 0
	v_mov_b64_e32 v[98:99], 0
	v_mov_b64_e32 v[100:101], 0
	v_mov_b64_e32 v[102:103], 0
	v_mov_b64_e32 v[104:105], 0
	v_mov_b64_e32 v[106:107], 0
	v_mov_b64_e32 v[108:109], 0
	v_mov_b64_e32 v[110:111], 0
	v_mov_b64_e32 v[112:113], 0
	v_mov_b64_e32 v[114:115], 0
	v_mov_b64_e32 v[116:117], 0
	v_mov_b64_e32 v[118:119], 0
	v_mov_b64_e32 v[120:121], 0
	v_mov_b64_e32 v[122:123], 0
	v_mov_b64_e32 v[124:125], 0
	v_mov_b64_e32 v[126:127], 0
